# accumulator zero-init with v_mov_b64 (64 instead of 128 moves per tile)
# speedup vs baseline: 1.0214x; 1.0039x over previous
.LBB0_34:
	s_ashr_i32 s41, s40, 31
	s_lshl_b64 s[18:19], s[40:41], 20
	s_add_u32 s2, s57, s18
	s_addc_u32 s11, s58, s19
	s_and_b64 s[8:9], s[8:9], exec
	s_cselect_b32 s67, s11, s1
	s_cselect_b32 s66, s2, s0
	s_add_u32 s11, s64, 0x100
	s_addc_u32 s13, s65, 0
	s_add_u32 s8, s0, 0x80080
	v_mov_b32_e32 v0, 0
	s_addc_u32 s9, s1, 0
	s_mov_b32 s15, -2
	v_mov_b64_e32 v[0:1], 0
	v_mov_b64_e32 v[2:3], 0
	v_mov_b64_e32 v[4:5], 0
	v_mov_b64_e32 v[6:7], 0
	v_mov_b64_e32 v[8:9], 0
	v_mov_b64_e32 v[10:11], 0
	v_mov_b64_e32 v[12:13], 0
	v_mov_b64_e32 v[14:15], 0
	v_mov_b64_e32 v[16:17], 0
	v_mov_b64_e32 v[18:19], 0
	v_mov_b64_e32 v[20:21], 0
	v_mov_b64_e32 v[22:23], 0
	v_mov_b64_e32 v[24:25], 0
	v_mov_b64_e32 v[26:27], 0
	v_mov_b64_e32 v[28:29], 0
	v_mov_b64_e32 v[30:31], 0
	v_mov_b64_e32 v[32:33], 0
	v_mov_b64_e32 v[34:35], 0
	v_mov_b64_e32 v[36:37], 0
	v_mov_b64_e32 v[38:39], 0
	v_mov_b64_e32 v[40:41], 0
	v_mov_b64_e32 v[42:43], 0
	v_mov_b64_e32 v[44:45], 0
	v_mov_b64_e32 v[46:47], 0
	v_mov_b64_e32 v[48:49], 0
	v_mov_b64_e32 v[50:51], 0
	v_mov_b64_e32 v[52:53], 0
	v_mov_b64_e32 v[54:55], 0
	v_mov_b64_e32 v[56:57], 0
	v_mov_b64_e32 v[58:59], 0
	v_mov_b64_e32 v[60:61], 0
	v_mov_b64_e32 v[62:63], 0
	v_mov_b64_e32 v[64:65], 0
	v_mov_b64_e32 v[66:67], 0
	v_mov_b64_e32 v[68:69], 0
	v_mov_b64_e32 v[70:71], 0
	v_mov_b64_e32 v[72:73], 0
	v_mov_b64_e32 v[74:75], 0
	v_mov_b64_e32 v[76:77], 0
	v_mov_b64_e32 v[78:79], 0
	v_mov_b64_e32 v[80:81], 0
	v_mov_b64_e32 v[82:83], 0
	v_mov_b64_e32 v[84:85], 0
	v_mov_b64_e32 v[86:87], 0
	v_mov_b64_e32 v[88:89], 0
	v_mov_b64_e32 v[90:91], 0
	v_mov_b64_e32 v[92:93], 0
	v_mov_b64_e32 v[94:95], 0
	v_mov_b64_e32 v[96:97], 0
	v_mov_b64_e32 v[98:99], 0
	v_mov_b64_e32 v[100:101], 0
	v_mov_b64_e32 v[102:103], 0
	v_mov_b64_e32 v[104:105], 0
	v_mov_b64_e32 v[106:107], 0
	v_mov_b64_e32 v[108:109], 0
	v_mov_b64_e32 v[110:111], 0
	v_mov_b64_e32 v[112:113], 0
	v_mov_b64_e32 v[114:115], 0
	v_mov_b64_e32 v[116:117], 0
	v_mov_b64_e32 v[118:119], 0
	v_mov_b64_e32 v[120:121], 0
	v_mov_b64_e32 v[122:123], 0
	v_mov_b64_e32 v[124:125], 0
	v_mov_b64_e32 v[126:127], 0

.LBB0_95:
	s_ashr_i32 s9, s8, 31
	v_cmp_lt_i64_e32 vcc, s[12:13], v[148:149]
	s_lshl_b64 s[12:13], s[8:9], 19
	s_add_u32 s2, s24, s12
	s_addc_u32 s9, s25, s13
	s_and_b64 s[12:13], vcc, exec
	s_cselect_b32 s13, s9, s1
	s_cselect_b32 s12, s2, s0
	s_ashr_i32 s11, s10, 31
	s_lshl_b64 s[14:15], s[10:11], 19
	s_add_u32 s2, s57, s14
	s_addc_u32 s9, s58, s15
	s_and_b64 s[14:15], vcc, exec
	s_cselect_b32 s15, s9, s41
	s_cselect_b32 s14, s2, s40
	s_add_u32 s9, s40, 0x100
	s_addc_u32 s11, s41, 0
	s_add_u32 s40, s0, 0x40080
	v_mov_b32_e32 v0, 0
	s_addc_u32 s41, s1, 0
	s_mov_b32 s72, -2
	v_mov_b64_e32 v[0:1], 0
	v_mov_b64_e32 v[2:3], 0
	v_mov_b64_e32 v[4:5], 0
	v_mov_b64_e32 v[6:7], 0
	v_mov_b64_e32 v[8:9], 0
	v_mov_b64_e32 v[10:11], 0
	v_mov_b64_e32 v[12:13], 0
	v_mov_b64_e32 v[14:15], 0
	v_mov_b64_e32 v[16:17], 0
	v_mov_b64_e32 v[18:19], 0
	v_mov_b64_e32 v[20:21], 0
	v_mov_b64_e32 v[22:23], 0
	v_mov_b64_e32 v[24:25], 0
	v_mov_b64_e32 v[26:27], 0
	v_mov_b64_e32 v[28:29], 0
	v_mov_b64_e32 v[30:31], 0
	v_mov_b64_e32 v[32:33], 0
	v_mov_b64_e32 v[34:35], 0
	v_mov_b64_e32 v[36:37], 0
	v_mov_b64_e32 v[38:39], 0
	v_mov_b64_e32 v[40:41], 0
	v_mov_b64_e32 v[42:43], 0
	v_mov_b64_e32 v[44:45], 0
	v_mov_b64_e32 v[46:47], 0
	v_mov_b64_e32 v[48:49], 0
	v_mov_b64_e32 v[50:51], 0
	v_mov_b64_e32 v[52:53], 0
	v_mov_b64_e32 v[54:55], 0
	v_mov_b64_e32 v[56:57], 0
	v_mov_b64_e32 v[58:59], 0
	v_mov_b64_e32 v[60:61], 0
	v_mov_b64_e32 v[62:63], 0
	v_mov_b64_e32 v[64:65], 0
	v_mov_b64_e32 v[66:67], 0
	v_mov_b64_e32 v[68:69], 0
	v_mov_b64_e32 v[70:71], 0
	v_mov_b64_e32 v[72:73], 0
	v_mov_b64_e32 v[74:75], 0
	v_mov_b64_e32 v[76:77], 0
	v_mov_b64_e32 v[78:79], 0
	v_mov_b64_e32 v[80:81], 0
	v_mov_b64_e32 v[82:83], 0
	v_mov_b64_e32 v[84:85], 0
	v_mov_b64_e32 v[86:87], 0
	v_mov_b64_e32 v[88:89], 0
	v_mov_b64_e32 v[90:91], 0
	v_mov_b64_e32 v[92:93], 0
	v_mov_b64_e32 v[94:95], 0
	v_mov_b64_e32 v[96:97], 0
	v_mov_b64_e32 v[98:99], 0
	v_mov_b64_e32 v[100:101], 0
	v_mov_b64_e32 v[102:103], 0
	v_mov_b64_e32 v[104:105], 0
	v_mov_b64_e32 v[106:107], 0
	v_mov_b64_e32 v[108:109], 0
	v_mov_b64_e32 v[110:111], 0
	v_mov_b64_e32 v[112:113], 0
	v_mov_b64_e32 v[114:115], 0
	v_mov_b64_e32 v[116:117], 0
	v_mov_b64_e32 v[118:119], 0
	v_mov_b64_e32 v[120:121], 0
	v_mov_b64_e32 v[122:123], 0
	v_mov_b64_e32 v[124:125], 0
	v_mov_b64_e32 v[126:127], 0

.LBB0_125:
	s_add_u32 s13, s68, 0x100
	s_addc_u32 s15, s69, 0
	s_add_u32 s8, s0, 0x80080
	v_mov_b32_e32 v0, 0
	s_addc_u32 s9, s1, 0
	s_mov_b32 s20, -2
	v_mov_b64_e32 v[0:1], 0
	v_mov_b64_e32 v[2:3], 0
	v_mov_b64_e32 v[4:5], 0
	v_mov_b64_e32 v[6:7], 0
	v_mov_b64_e32 v[8:9], 0
	v_mov_b64_e32 v[10:11], 0
	v_mov_b64_e32 v[12:13], 0
	v_mov_b64_e32 v[14:15], 0
	v_mov_b64_e32 v[16:17], 0
	v_mov_b64_e32 v[18:19], 0
	v_mov_b64_e32 v[20:21], 0
	v_mov_b64_e32 v[22:23], 0
	v_mov_b64_e32 v[24:25], 0
	v_mov_b64_e32 v[26:27], 0
	v_mov_b64_e32 v[28:29], 0
	v_mov_b64_e32 v[30:31], 0
	v_mov_b64_e32 v[32:33], 0
	v_mov_b64_e32 v[34:35], 0
	v_mov_b64_e32 v[36:37], 0
	v_mov_b64_e32 v[38:39], 0
	v_mov_b64_e32 v[40:41], 0
	v_mov_b64_e32 v[42:43], 0
	v_mov_b64_e32 v[44:45], 0
	v_mov_b64_e32 v[46:47], 0
	v_mov_b64_e32 v[48:49], 0
	v_mov_b64_e32 v[50:51], 0
	v_mov_b64_e32 v[52:53], 0
	v_mov_b64_e32 v[54:55], 0
	v_mov_b64_e32 v[56:57], 0
	v_mov_b64_e32 v[58:59], 0
	v_mov_b64_e32 v[60:61], 0
	v_mov_b64_e32 v[62:63], 0
	v_mov_b64_e32 v[64:65], 0
	v_mov_b64_e32 v[66:67], 0
	v_mov_b64_e32 v[68:69], 0
	v_mov_b64_e32 v[70:71], 0
	v_mov_b64_e32 v[72:73], 0
	v_mov_b64_e32 v[74:75], 0
	v_mov_b64_e32 v[76:77], 0
	v_mov_b64_e32 v[78:79], 0
	v_mov_b64_e32 v[80:81], 0
	v_mov_b64_e32 v[82:83], 0
	v_mov_b64_e32 v[84:85], 0
	v_mov_b64_e32 v[86:87], 0
	v_mov_b64_e32 v[88:89], 0
	v_mov_b64_e32 v[90:91], 0
	v_mov_b64_e32 v[92:93], 0
	v_mov_b64_e32 v[94:95], 0
	v_mov_b64_e32 v[96:97], 0
	v_mov_b64_e32 v[98:99], 0
	v_mov_b64_e32 v[100:101], 0
	v_mov_b64_e32 v[102:103], 0
	v_mov_b64_e32 v[104:105], 0
	v_mov_b64_e32 v[106:107], 0
	v_mov_b64_e32 v[108:109], 0
	v_mov_b64_e32 v[110:111], 0
	v_mov_b64_e32 v[112:113], 0
	v_mov_b64_e32 v[114:115], 0
	v_mov_b64_e32 v[116:117], 0
	v_mov_b64_e32 v[118:119], 0
	v_mov_b64_e32 v[120:121], 0
	v_mov_b64_e32 v[122:123], 0
	v_mov_b64_e32 v[124:125], 0
	v_mov_b64_e32 v[126:127], 0

.LBB0_168:
	s_ashr_i32 s45, s44, 31
	s_lshl_b64 s[18:19], s[44:45], 20
	v_readlane_b32 s30, v252, 25
	v_readlane_b32 s31, v252, 26
	s_add_u32 s2, s30, s18
	s_addc_u32 s17, s31, s19
	s_and_b64 s[8:9], s[8:9], exec
	s_cselect_b32 s9, s17, s1
	s_cselect_b32 s8, s2, s0
	s_add_u32 s17, s66, 0x100
	s_addc_u32 s41, s67, 0
	s_add_u32 s66, s0, 0x80080
	v_mov_b32_e32 v0, 0
	s_addc_u32 s67, s1, 0
	s_mov_b32 s45, -2
	v_mov_b64_e32 v[0:1], 0
	v_mov_b64_e32 v[2:3], 0
	v_mov_b64_e32 v[4:5], 0
	v_mov_b64_e32 v[6:7], 0
	v_mov_b64_e32 v[8:9], 0
	v_mov_b64_e32 v[10:11], 0
	v_mov_b64_e32 v[12:13], 0
	v_mov_b64_e32 v[14:15], 0
	v_mov_b64_e32 v[16:17], 0
	v_mov_b64_e32 v[18:19], 0
	v_mov_b64_e32 v[20:21], 0
	v_mov_b64_e32 v[22:23], 0
	v_mov_b64_e32 v[24:25], 0
	v_mov_b64_e32 v[26:27], 0
	v_mov_b64_e32 v[28:29], 0
	v_mov_b64_e32 v[30:31], 0
	v_mov_b64_e32 v[32:33], 0
	v_mov_b64_e32 v[34:35], 0
	v_mov_b64_e32 v[36:37], 0
	v_mov_b64_e32 v[38:39], 0
	v_mov_b64_e32 v[40:41], 0
	v_mov_b64_e32 v[42:43], 0
	v_mov_b64_e32 v[44:45], 0
	v_mov_b64_e32 v[46:47], 0
	v_mov_b64_e32 v[48:49], 0
	v_mov_b64_e32 v[50:51], 0
	v_mov_b64_e32 v[52:53], 0
	v_mov_b64_e32 v[54:55], 0
	v_mov_b64_e32 v[56:57], 0
	v_mov_b64_e32 v[58:59], 0
	v_mov_b64_e32 v[60:61], 0
	v_mov_b64_e32 v[62:63], 0
	v_mov_b64_e32 v[64:65], 0
	v_mov_b64_e32 v[66:67], 0
	v_mov_b64_e32 v[68:69], 0
	v_mov_b64_e32 v[70:71], 0
	v_mov_b64_e32 v[72:73], 0
	v_mov_b64_e32 v[74:75], 0
	v_mov_b64_e32 v[76:77], 0
	v_mov_b64_e32 v[78:79], 0
	v_mov_b64_e32 v[80:81], 0
	v_mov_b64_e32 v[82:83], 0
	v_mov_b64_e32 v[84:85], 0
	v_mov_b64_e32 v[86:87], 0
	v_mov_b64_e32 v[88:89], 0
	v_mov_b64_e32 v[90:91], 0
	v_mov_b64_e32 v[92:93], 0
	v_mov_b64_e32 v[94:95], 0
	v_mov_b64_e32 v[96:97], 0
	v_mov_b64_e32 v[98:99], 0
	v_mov_b64_e32 v[100:101], 0
	v_mov_b64_e32 v[102:103], 0
	v_mov_b64_e32 v[104:105], 0
	v_mov_b64_e32 v[106:107], 0
	v_mov_b64_e32 v[108:109], 0
	v_mov_b64_e32 v[110:111], 0
	v_mov_b64_e32 v[112:113], 0
	v_mov_b64_e32 v[114:115], 0
	v_mov_b64_e32 v[116:117], 0
	v_mov_b64_e32 v[118:119], 0
	v_mov_b64_e32 v[120:121], 0
	v_mov_b64_e32 v[122:123], 0
	v_mov_b64_e32 v[124:125], 0
	v_mov_b64_e32 v[126:127], 0

.LBB0_202:
	v_mov_b32_e32 v0, 0
	s_mov_b32 s13, 0
	s_mov_b64 s[66:67], -1
	s_mov_b64 s[0:1], 0
	v_mov_b64_e32 v[0:1], 0
	v_mov_b64_e32 v[2:3], 0
	v_mov_b64_e32 v[4:5], 0
	v_mov_b64_e32 v[6:7], 0
	v_mov_b64_e32 v[8:9], 0
	v_mov_b64_e32 v[10:11], 0
	v_mov_b64_e32 v[12:13], 0
	v_mov_b64_e32 v[14:15], 0
	v_mov_b64_e32 v[16:17], 0
	v_mov_b64_e32 v[18:19], 0
	v_mov_b64_e32 v[20:21], 0
	v_mov_b64_e32 v[22:23], 0
	v_mov_b64_e32 v[24:25], 0
	v_mov_b64_e32 v[26:27], 0
	v_mov_b64_e32 v[28:29], 0
	v_mov_b64_e32 v[30:31], 0
	v_mov_b64_e32 v[32:33], 0
	v_mov_b64_e32 v[34:35], 0
	v_mov_b64_e32 v[36:37], 0
	v_mov_b64_e32 v[38:39], 0
	v_mov_b64_e32 v[40:41], 0
	v_mov_b64_e32 v[42:43], 0
	v_mov_b64_e32 v[44:45], 0
	v_mov_b64_e32 v[46:47], 0
	v_mov_b64_e32 v[48:49], 0
	v_mov_b64_e32 v[50:51], 0
	v_mov_b64_e32 v[52:53], 0
	v_mov_b64_e32 v[54:55], 0
	v_mov_b64_e32 v[56:57], 0
	v_mov_b64_e32 v[58:59], 0
	v_mov_b64_e32 v[60:61], 0
	v_mov_b64_e32 v[62:63], 0
	v_mov_b64_e32 v[64:65], 0
	v_mov_b64_e32 v[66:67], 0
	v_mov_b64_e32 v[68:69], 0
	v_mov_b64_e32 v[70:71], 0
	v_mov_b64_e32 v[72:73], 0
	v_mov_b64_e32 v[74:75], 0
	v_mov_b64_e32 v[76:77], 0
	v_mov_b64_e32 v[78:79], 0
	v_mov_b64_e32 v[80:81], 0
	v_mov_b64_e32 v[82:83], 0
	v_mov_b64_e32 v[84:85], 0
	v_mov_b64_e32 v[86:87], 0
	v_mov_b64_e32 v[88:89], 0
	v_mov_b64_e32 v[90:91], 0
	v_mov_b64_e32 v[92:93], 0
	v_mov_b64_e32 v[94:95], 0
	v_mov_b64_e32 v[96:97], 0
	v_mov_b64_e32 v[98:99], 0
	v_mov_b64_e32 v[100:101], 0
	v_mov_b64_e32 v[102:103], 0
	v_mov_b64_e32 v[104:105], 0
	v_mov_b64_e32 v[106:107], 0
	v_mov_b64_e32 v[108:109], 0
	v_mov_b64_e32 v[110:111], 0
	v_mov_b64_e32 v[112:113], 0
	v_mov_b64_e32 v[114:115], 0
	v_mov_b64_e32 v[116:117], 0
	v_mov_b64_e32 v[118:119], 0
	v_mov_b64_e32 v[120:121], 0
	v_mov_b64_e32 v[122:123], 0
	v_mov_b64_e32 v[124:125], 0
	v_mov_b64_e32 v[126:127], 0

.LBB0_274:
	s_add_u32 s59, s0, 0x100
	v_mov_b32_e32 v0, 0
	s_addc_u32 s64, s1, 0
	s_mov_b32 s65, -2
	v_mov_b64_e32 v[0:1], 0
	v_mov_b64_e32 v[2:3], 0
	v_mov_b64_e32 v[4:5], 0
	v_mov_b64_e32 v[6:7], 0
	v_mov_b64_e32 v[8:9], 0
	v_mov_b64_e32 v[10:11], 0
	v_mov_b64_e32 v[12:13], 0
	v_mov_b64_e32 v[14:15], 0
	v_mov_b64_e32 v[16:17], 0
	v_mov_b64_e32 v[18:19], 0
	v_mov_b64_e32 v[20:21], 0
	v_mov_b64_e32 v[22:23], 0
	v_mov_b64_e32 v[24:25], 0
	v_mov_b64_e32 v[26:27], 0
	v_mov_b64_e32 v[28:29], 0
	v_mov_b64_e32 v[30:31], 0
	v_mov_b64_e32 v[32:33], 0
	v_mov_b64_e32 v[34:35], 0
	v_mov_b64_e32 v[36:37], 0
	v_mov_b64_e32 v[38:39], 0
	v_mov_b64_e32 v[40:41], 0
	v_mov_b64_e32 v[42:43], 0
	v_mov_b64_e32 v[44:45], 0
	v_mov_b64_e32 v[46:47], 0
	v_mov_b64_e32 v[48:49], 0
	v_mov_b64_e32 v[50:51], 0
	v_mov_b64_e32 v[52:53], 0
	v_mov_b64_e32 v[54:55], 0
	v_mov_b64_e32 v[56:57], 0
	v_mov_b64_e32 v[58:59], 0
	v_mov_b64_e32 v[60:61], 0
	v_mov_b64_e32 v[62:63], 0
	v_mov_b64_e32 v[64:65], 0
	v_mov_b64_e32 v[66:67], 0
	v_mov_b64_e32 v[68:69], 0
	v_mov_b64_e32 v[70:71], 0
	v_mov_b64_e32 v[72:73], 0
	v_mov_b64_e32 v[74:75], 0
	v_mov_b64_e32 v[76:77], 0
	v_mov_b64_e32 v[78:79], 0
	v_mov_b64_e32 v[80:81], 0
	v_mov_b64_e32 v[82:83], 0
	v_mov_b64_e32 v[84:85], 0
	v_mov_b64_e32 v[86:87], 0
	v_mov_b64_e32 v[88:89], 0
	v_mov_b64_e32 v[90:91], 0
	v_mov_b64_e32 v[92:93], 0
	v_mov_b64_e32 v[94:95], 0
	v_mov_b64_e32 v[96:97], 0
	v_mov_b64_e32 v[98:99], 0
	v_mov_b64_e32 v[100:101], 0
	v_mov_b64_e32 v[102:103], 0
	v_mov_b64_e32 v[104:105], 0
	v_mov_b64_e32 v[106:107], 0
	v_mov_b64_e32 v[108:109], 0
	v_mov_b64_e32 v[110:111], 0
	v_mov_b64_e32 v[112:113], 0
	v_mov_b64_e32 v[114:115], 0
	v_mov_b64_e32 v[116:117], 0
	v_mov_b64_e32 v[118:119], 0
	v_mov_b64_e32 v[120:121], 0
	v_mov_b64_e32 v[122:123], 0
	v_mov_b64_e32 v[124:125], 0
	v_mov_b64_e32 v[126:127], 0

.LBB0_288:
	v_mov_b64_e32 v[0:1], 0xb00
	s_ashr_i32 s5, s4, 31
	v_cmp_lt_i64_e32 vcc, s[10:11], v[0:1]
	s_lshl_b64 s[10:11], s[4:5], 19
	s_add_u32 s2, s22, s10
	s_addc_u32 s5, s23, s11
	s_and_b64 s[10:11], vcc, exec
	s_cselect_b32 s11, s5, s1
	s_cselect_b32 s10, s2, s0
	s_ashr_i32 s9, s8, 31
	s_lshl_b64 s[12:13], s[8:9], 19
	s_add_u32 s2, s40, s12
	s_addc_u32 s5, s41, s13
	s_and_b64 s[12:13], vcc, exec
	s_cselect_b32 s13, s5, s17
	s_cselect_b32 s12, s2, s16
	s_add_u32 s5, s16, 0x100
	s_addc_u32 s9, s17, 0
	s_add_u32 s16, s0, 0x40080
	v_mov_b32_e32 v0, 0
	s_addc_u32 s17, s1, 0
	s_mov_b32 s21, -2
	v_mov_b64_e32 v[0:1], 0
	v_mov_b64_e32 v[2:3], 0
	v_mov_b64_e32 v[4:5], 0
	v_mov_b64_e32 v[6:7], 0
	v_mov_b64_e32 v[8:9], 0
	v_mov_b64_e32 v[10:11], 0
	v_mov_b64_e32 v[12:13], 0
	v_mov_b64_e32 v[14:15], 0
	v_mov_b64_e32 v[16:17], 0
	v_mov_b64_e32 v[18:19], 0
	v_mov_b64_e32 v[20:21], 0
	v_mov_b64_e32 v[22:23], 0
	v_mov_b64_e32 v[24:25], 0
	v_mov_b64_e32 v[26:27], 0
	v_mov_b64_e32 v[28:29], 0
	v_mov_b64_e32 v[30:31], 0
	v_mov_b64_e32 v[32:33], 0
	v_mov_b64_e32 v[34:35], 0
	v_mov_b64_e32 v[36:37], 0
	v_mov_b64_e32 v[38:39], 0
	v_mov_b64_e32 v[40:41], 0
	v_mov_b64_e32 v[42:43], 0
	v_mov_b64_e32 v[44:45], 0
	v_mov_b64_e32 v[46:47], 0
	v_mov_b64_e32 v[48:49], 0
	v_mov_b64_e32 v[50:51], 0
	v_mov_b64_e32 v[52:53], 0
	v_mov_b64_e32 v[54:55], 0
	v_mov_b64_e32 v[56:57], 0
	v_mov_b64_e32 v[58:59], 0
	v_mov_b64_e32 v[60:61], 0
	v_mov_b64_e32 v[62:63], 0
	v_mov_b64_e32 v[64:65], 0
	v_mov_b64_e32 v[66:67], 0
	v_mov_b64_e32 v[68:69], 0
	v_mov_b64_e32 v[70:71], 0
	v_mov_b64_e32 v[72:73], 0
	v_mov_b64_e32 v[74:75], 0
	v_mov_b64_e32 v[76:77], 0
	v_mov_b64_e32 v[78:79], 0
	v_mov_b64_e32 v[80:81], 0
	v_mov_b64_e32 v[82:83], 0
	v_mov_b64_e32 v[84:85], 0
	v_mov_b64_e32 v[86:87], 0
	v_mov_b64_e32 v[88:89], 0
	v_mov_b64_e32 v[90:91], 0
	v_mov_b64_e32 v[92:93], 0
	v_mov_b64_e32 v[94:95], 0
	v_mov_b64_e32 v[96:97], 0
	v_mov_b64_e32 v[98:99], 0
	v_mov_b64_e32 v[100:101], 0
	v_mov_b64_e32 v[102:103], 0
	v_mov_b64_e32 v[104:105], 0
	v_mov_b64_e32 v[106:107], 0
	v_mov_b64_e32 v[108:109], 0
	v_mov_b64_e32 v[110:111], 0
	v_mov_b64_e32 v[112:113], 0
	v_mov_b64_e32 v[114:115], 0
	v_mov_b64_e32 v[116:117], 0
	v_mov_b64_e32 v[118:119], 0
	v_mov_b64_e32 v[120:121], 0
	v_mov_b64_e32 v[122:123], 0
	v_mov_b64_e32 v[124:125], 0
	v_mov_b64_e32 v[126:127], 0

.LBB0_320:
	s_ashr_i32 s5, s4, 31
	v_cmp_lt_i64_e32 vcc, s[10:11], v[148:149]
	s_lshl_b64 s[10:11], s[4:5], 19
	s_add_u32 s2, s22, s10
	s_addc_u32 s5, s23, s11
	s_and_b64 s[10:11], vcc, exec
	s_cselect_b32 s11, s5, s1
	s_cselect_b32 s10, s2, s0
	s_ashr_i32 s9, s8, 31
	s_lshl_b64 s[12:13], s[8:9], 19
	s_add_u32 s2, s39, s12
	s_addc_u32 s5, s44, s13
	s_and_b64 s[12:13], vcc, exec
	s_cselect_b32 s13, s5, s17
	s_cselect_b32 s12, s2, s16
	s_add_u32 s5, s16, 0x100
	s_addc_u32 s9, s17, 0
	s_add_u32 s16, s0, 0x40080
	v_mov_b32_e32 v0, 0
	s_addc_u32 s17, s1, 0
	s_mov_b32 s59, -2
	v_mov_b64_e32 v[0:1], 0
	v_mov_b64_e32 v[2:3], 0
	v_mov_b64_e32 v[4:5], 0
	v_mov_b64_e32 v[6:7], 0
	v_mov_b64_e32 v[8:9], 0
	v_mov_b64_e32 v[10:11], 0
	v_mov_b64_e32 v[12:13], 0
	v_mov_b64_e32 v[14:15], 0
	v_mov_b64_e32 v[16:17], 0
	v_mov_b64_e32 v[18:19], 0
	v_mov_b64_e32 v[20:21], 0
	v_mov_b64_e32 v[22:23], 0
	v_mov_b64_e32 v[24:25], 0
	v_mov_b64_e32 v[26:27], 0
	v_mov_b64_e32 v[28:29], 0
	v_mov_b64_e32 v[30:31], 0
	v_mov_b64_e32 v[32:33], 0
	v_mov_b64_e32 v[34:35], 0
	v_mov_b64_e32 v[36:37], 0
	v_mov_b64_e32 v[38:39], 0
	v_mov_b64_e32 v[40:41], 0
	v_mov_b64_e32 v[42:43], 0
	v_mov_b64_e32 v[44:45], 0
	v_mov_b64_e32 v[46:47], 0
	v_mov_b64_e32 v[48:49], 0
	v_mov_b64_e32 v[50:51], 0
	v_mov_b64_e32 v[52:53], 0
	v_mov_b64_e32 v[54:55], 0
	v_mov_b64_e32 v[56:57], 0
	v_mov_b64_e32 v[58:59], 0
	v_mov_b64_e32 v[60:61], 0
	v_mov_b64_e32 v[62:63], 0
	v_mov_b64_e32 v[64:65], 0
	v_mov_b64_e32 v[66:67], 0
	v_mov_b64_e32 v[68:69], 0
	v_mov_b64_e32 v[70:71], 0
	v_mov_b64_e32 v[72:73], 0
	v_mov_b64_e32 v[74:75], 0
	v_mov_b64_e32 v[76:77], 0
	v_mov_b64_e32 v[78:79], 0
	v_mov_b64_e32 v[80:81], 0
	v_mov_b64_e32 v[82:83], 0
	v_mov_b64_e32 v[84:85], 0
	v_mov_b64_e32 v[86:87], 0
	v_mov_b64_e32 v[88:89], 0
	v_mov_b64_e32 v[90:91], 0
	v_mov_b64_e32 v[92:93], 0
	v_mov_b64_e32 v[94:95], 0
	v_mov_b64_e32 v[96:97], 0
	v_mov_b64_e32 v[98:99], 0
	v_mov_b64_e32 v[100:101], 0
	v_mov_b64_e32 v[102:103], 0
	v_mov_b64_e32 v[104:105], 0
	v_mov_b64_e32 v[106:107], 0
	v_mov_b64_e32 v[108:109], 0
	v_mov_b64_e32 v[110:111], 0
	v_mov_b64_e32 v[112:113], 0
	v_mov_b64_e32 v[114:115], 0
	v_mov_b64_e32 v[116:117], 0
	v_mov_b64_e32 v[118:119], 0
	v_mov_b64_e32 v[120:121], 0
	v_mov_b64_e32 v[122:123], 0
	v_mov_b64_e32 v[124:125], 0
	v_mov_b64_e32 v[126:127], 0

.LBB0_403:
	v_mov_b32_e32 v123, 0
	s_andn2_b64 vcc, exec, s[80:81]
	v_mov_b32_e32 v122, v123
	v_mov_b32_e32 v121, v123
	v_mov_b32_e32 v120, v123
	v_mov_b32_e32 v71, v123
	v_mov_b32_e32 v70, v123
	v_mov_b32_e32 v69, v123
	v_mov_b32_e32 v68, v123
	v_mov_b32_e32 v119, v123
	v_mov_b32_e32 v118, v123
	v_mov_b32_e32 v117, v123
	v_mov_b32_e32 v116, v123
	v_mov_b32_e32 v63, v123
	v_mov_b32_e32 v62, v123
	v_mov_b32_e32 v61, v123
	v_mov_b32_e32 v60, v123
	v_mov_b32_e32 v111, v123
	v_mov_b32_e32 v110, v123
	v_mov_b32_e32 v109, v123
	v_mov_b32_e32 v108, v123
	v_mov_b32_e32 v47, v123
	v_mov_b32_e32 v46, v123
	v_mov_b32_e32 v45, v123
	v_mov_b32_e32 v44, v123
	v_mov_b32_e32 v103, v123
	v_mov_b32_e32 v102, v123
	v_mov_b32_e32 v101, v123
	v_mov_b32_e32 v100, v123
	v_mov_b32_e32 v39, v123
	v_mov_b32_e32 v38, v123
	v_mov_b32_e32 v37, v123
	v_mov_b32_e32 v36, v123
	v_mov_b32_e32 v127, v123
	v_mov_b32_e32 v126, v123
	v_mov_b32_e32 v125, v123
	v_mov_b32_e32 v124, v123
	v_mov_b32_e32 v67, v123
	v_mov_b32_e32 v66, v123
	v_mov_b32_e32 v65, v123
	v_mov_b32_e32 v64, v123
	v_mov_b32_e32 v115, v123
	v_mov_b32_e32 v114, v123
	v_mov_b32_e32 v113, v123
	v_mov_b32_e32 v112, v123
	v_mov_b32_e32 v59, v123
	v_mov_b32_e32 v58, v123
	v_mov_b32_e32 v57, v123
	v_mov_b32_e32 v56, v123
	v_mov_b32_e32 v107, v123
	v_mov_b32_e32 v106, v123
	v_mov_b32_e32 v105, v123
	v_mov_b32_e32 v104, v123
	v_mov_b32_e32 v43, v123
	v_mov_b32_e32 v42, v123
	v_mov_b32_e32 v41, v123
	v_mov_b32_e32 v40, v123
	v_mov_b32_e32 v99, v123
	v_mov_b32_e32 v98, v123
	v_mov_b32_e32 v97, v123
	v_mov_b32_e32 v96, v123
	v_mov_b32_e32 v35, v123
	v_mov_b32_e32 v34, v123
	v_mov_b32_e32 v33, v123
	v_mov_b32_e32 v32, v123
	v_mov_b32_e32 v95, v123
	v_mov_b32_e32 v94, v123
	v_mov_b32_e32 v93, v123
	v_mov_b32_e32 v92, v123
	v_mov_b32_e32 v31, v123
	v_mov_b32_e32 v30, v123
	v_mov_b32_e32 v29, v123
	v_mov_b32_e32 v28, v123
	v_mov_b32_e32 v87, v123
	v_mov_b32_e32 v86, v123
	v_mov_b32_e32 v85, v123
	v_mov_b32_e32 v84, v123
	v_mov_b32_e32 v23, v123
	v_mov_b32_e32 v22, v123
	v_mov_b32_e32 v21, v123
	v_mov_b32_e32 v20, v123
	v_mov_b32_e32 v79, v123
	v_mov_b32_e32 v78, v123
	v_mov_b32_e32 v77, v123
	v_mov_b32_e32 v76, v123
	v_mov_b32_e32 v15, v123
	v_mov_b32_e32 v14, v123
	v_mov_b32_e32 v13, v123
	v_mov_b32_e32 v12, v123
	v_mov_b32_e32 v55, v123
	v_mov_b32_e32 v54, v123
	v_mov_b32_e32 v53, v123
	v_mov_b32_e32 v52, v123
	v_mov_b32_e32 v7, v123
	v_mov_b32_e32 v6, v123
	v_mov_b32_e32 v5, v123
	v_mov_b32_e32 v4, v123
	v_mov_b32_e32 v91, v123
	v_mov_b32_e32 v90, v123
	v_mov_b32_e32 v89, v123
	v_mov_b32_e32 v88, v123
	v_mov_b32_e32 v27, v123
	v_mov_b32_e32 v26, v123
	v_mov_b32_e32 v25, v123
	v_mov_b32_e32 v24, v123
	v_mov_b32_e32 v83, v123
	v_mov_b32_e32 v82, v123
	v_mov_b32_e32 v81, v123
	v_mov_b32_e32 v80, v123
	v_mov_b32_e32 v19, v123
	v_mov_b32_e32 v18, v123
	v_mov_b32_e32 v17, v123
	v_mov_b32_e32 v16, v123
	v_mov_b32_e32 v75, v123
	v_mov_b32_e32 v74, v123
	v_mov_b32_e32 v73, v123
	v_mov_b32_e32 v72, v123
	v_mov_b32_e32 v11, v123
	v_mov_b32_e32 v10, v123
	v_mov_b32_e32 v9, v123
	v_mov_b32_e32 v8, v123
	v_mov_b32_e32 v51, v123
	v_mov_b32_e32 v50, v123
	v_mov_b32_e32 v49, v123
	v_mov_b32_e32 v48, v123
	v_mov_b32_e32 v3, v123
	v_mov_b32_e32 v2, v123
	v_mov_b32_e32 v1, v123
	v_mov_b32_e32 v0, v123
	s_cbranch_vccnz .LBB0_392
	s_add_u32 s17, s0, 0x100
	s_addc_u32 s20, s1, 0
	s_add_u32 vcc_lo, s88, 0x20080
	v_mov_b32_e32 v0, 0
	s_addc_u32 vcc_hi, s89, 0
	s_mov_b32 s0, 0
	v_mov_b64_e32 v[0:1], 0
	v_mov_b64_e32 v[2:3], 0
	v_mov_b64_e32 v[4:5], 0
	v_mov_b64_e32 v[6:7], 0
	v_mov_b64_e32 v[8:9], 0
	v_mov_b64_e32 v[10:11], 0
	v_mov_b64_e32 v[12:13], 0
	v_mov_b64_e32 v[14:15], 0
	v_mov_b64_e32 v[16:17], 0
	v_mov_b64_e32 v[18:19], 0
	v_mov_b64_e32 v[20:21], 0
	v_mov_b64_e32 v[22:23], 0
	v_mov_b64_e32 v[24:25], 0
	v_mov_b64_e32 v[26:27], 0
	v_mov_b64_e32 v[28:29], 0
	v_mov_b64_e32 v[30:31], 0
	v_mov_b64_e32 v[32:33], 0
	v_mov_b64_e32 v[34:35], 0
	v_mov_b64_e32 v[36:37], 0
	v_mov_b64_e32 v[38:39], 0
	v_mov_b64_e32 v[40:41], 0
	v_mov_b64_e32 v[42:43], 0
	v_mov_b64_e32 v[44:45], 0
	v_mov_b64_e32 v[46:47], 0
	v_mov_b64_e32 v[48:49], 0
	v_mov_b64_e32 v[50:51], 0
	v_mov_b64_e32 v[52:53], 0
	v_mov_b64_e32 v[54:55], 0
	v_mov_b64_e32 v[56:57], 0
	v_mov_b64_e32 v[58:59], 0
	v_mov_b64_e32 v[60:61], 0
	v_mov_b64_e32 v[62:63], 0
	v_mov_b64_e32 v[64:65], 0
	v_mov_b64_e32 v[66:67], 0
	v_mov_b64_e32 v[68:69], 0
	v_mov_b64_e32 v[70:71], 0
	v_mov_b64_e32 v[72:73], 0
	v_mov_b64_e32 v[74:75], 0
	v_mov_b64_e32 v[76:77], 0
	v_mov_b64_e32 v[78:79], 0
	v_mov_b64_e32 v[80:81], 0
	v_mov_b64_e32 v[82:83], 0
	v_mov_b64_e32 v[84:85], 0
	v_mov_b64_e32 v[86:87], 0
	v_mov_b64_e32 v[88:89], 0
	v_mov_b64_e32 v[90:91], 0
	v_mov_b64_e32 v[92:93], 0
	v_mov_b64_e32 v[94:95], 0
	v_mov_b64_e32 v[96:97], 0
	v_mov_b64_e32 v[98:99], 0
	v_mov_b64_e32 v[100:101], 0
	v_mov_b64_e32 v[102:103], 0
	v_mov_b64_e32 v[104:105], 0
	v_mov_b64_e32 v[106:107], 0
	v_mov_b64_e32 v[108:109], 0
	v_mov_b64_e32 v[110:111], 0
	v_mov_b64_e32 v[112:113], 0
	v_mov_b64_e32 v[114:115], 0
	v_mov_b64_e32 v[116:117], 0
	v_mov_b64_e32 v[118:119], 0
	v_mov_b64_e32 v[120:121], 0
	v_mov_b64_e32 v[122:123], 0
	v_mov_b64_e32 v[124:125], 0
	v_mov_b64_e32 v[126:127], 0

.LBB0_506:
	s_add_u32 s17, s30, 0x100
	s_addc_u32 s19, s31, 0
	s_add_u32 s8, s0, 0x40080
	v_mov_b32_e32 v0, 0
	s_addc_u32 s9, s1, 0
	s_mov_b32 s21, -2
	v_mov_b64_e32 v[0:1], 0
	v_mov_b64_e32 v[2:3], 0
	v_mov_b64_e32 v[4:5], 0
	v_mov_b64_e32 v[6:7], 0
	v_mov_b64_e32 v[8:9], 0
	v_mov_b64_e32 v[10:11], 0
	v_mov_b64_e32 v[12:13], 0
	v_mov_b64_e32 v[14:15], 0
	v_mov_b64_e32 v[16:17], 0
	v_mov_b64_e32 v[18:19], 0
	v_mov_b64_e32 v[20:21], 0
	v_mov_b64_e32 v[22:23], 0
	v_mov_b64_e32 v[24:25], 0
	v_mov_b64_e32 v[26:27], 0
	v_mov_b64_e32 v[28:29], 0
	v_mov_b64_e32 v[30:31], 0
	v_mov_b64_e32 v[32:33], 0
	v_mov_b64_e32 v[34:35], 0
	v_mov_b64_e32 v[36:37], 0
	v_mov_b64_e32 v[38:39], 0
	v_mov_b64_e32 v[40:41], 0
	v_mov_b64_e32 v[42:43], 0
	v_mov_b64_e32 v[44:45], 0
	v_mov_b64_e32 v[46:47], 0
	v_mov_b64_e32 v[48:49], 0
	v_mov_b64_e32 v[50:51], 0
	v_mov_b64_e32 v[52:53], 0
	v_mov_b64_e32 v[54:55], 0
	v_mov_b64_e32 v[56:57], 0
	v_mov_b64_e32 v[58:59], 0
	v_mov_b64_e32 v[60:61], 0
	v_mov_b64_e32 v[62:63], 0
	v_mov_b64_e32 v[64:65], 0
	v_mov_b64_e32 v[66:67], 0
	v_mov_b64_e32 v[68:69], 0
	v_mov_b64_e32 v[70:71], 0
	v_mov_b64_e32 v[72:73], 0
	v_mov_b64_e32 v[74:75], 0
	v_mov_b64_e32 v[76:77], 0
	v_mov_b64_e32 v[78:79], 0
	v_mov_b64_e32 v[80:81], 0
	v_mov_b64_e32 v[82:83], 0
	v_mov_b64_e32 v[84:85], 0
	v_mov_b64_e32 v[86:87], 0
	v_mov_b64_e32 v[88:89], 0
	v_mov_b64_e32 v[90:91], 0
	v_mov_b64_e32 v[92:93], 0
	v_mov_b64_e32 v[94:95], 0
	v_mov_b64_e32 v[96:97], 0
	v_mov_b64_e32 v[98:99], 0
	v_mov_b64_e32 v[100:101], 0
	v_mov_b64_e32 v[102:103], 0
	v_mov_b64_e32 v[104:105], 0
	v_mov_b64_e32 v[106:107], 0
	v_mov_b64_e32 v[108:109], 0
	v_mov_b64_e32 v[110:111], 0
	v_mov_b64_e32 v[112:113], 0
	v_mov_b64_e32 v[114:115], 0
	v_mov_b64_e32 v[116:117], 0
	v_mov_b64_e32 v[118:119], 0
	v_mov_b64_e32 v[120:121], 0
	v_mov_b64_e32 v[122:123], 0
	v_mov_b64_e32 v[124:125], 0
	v_mov_b64_e32 v[126:127], 0
